# P5: CUs 0-63 run the sample-row out-proj unit first (no serial tail, de-synchronised epilogue bursts)
# baseline (speedup 1.0000x reference)
; #define PG8_BAR __builtin_amdgcn_s_barrier()
; template <class Epi, class Sched, bool ALIGN_EPI, bool SP2>
; __device__ __forceinline__ void gemm_phase(LAS unsigned char* lds, const Gemm g, const Sched& S, const Epi& E) {
;     ...
;     const int wid = __builtin_amdgcn_readfirstlane(tid >> 6), lane = tid & 63, wr = wid >> 2, wc = wid & 3, fr = lane & 15, fq = lane >> 4;
;     const int K = g.K, nt = K / BK, lda = g.lda;
;     unsigned voffA[2], voffB[2];
; #pragma unroll
;     for (int i = 0; i < 2; ++i) { int R, C; stage_rc(tid * 16 + i * 8192, R, C); const int Rb = (R & ~31) + perm32(R & 31);
;         voffA[i] = (unsigned)(R * lda + C) * 2u; voffB[i] = (unsigned)(Rb * g.ldb + C) * 2u; }
;     const size_t kstep = (size_t)(BK * 2);
;     const size_t hstepA = (size_t)HALF * lda * 2, hstepB = (size_t)HALF * g.ldb * 2;
;     const size_t tstepA = 2 * hstepA, tstepB = 2 * hstepB;
;     const unsigned ldsw = (unsigned)wid * 1024u;
;     const int aoff = lds_byte(wr * 64 + fr, fq * 8), boff = lds_byte(wc * 32 + fr, fq * 8);
;     ...
;     Unit cur, nxt; int ui = 0;
;     if (!S.next(0, cur)) return;
;     f32x4 acc[2][2][4][2];
; #pragma unroll
;     for (int a = 0; a < 2; ++a)
; #pragma unroll
;         for (int b = 0; b < 2; ++b)
; #pragma unroll
;             for (int m = 0; m < 4; ++m)
; #pragma unroll
;                 for (int n = 0; n < 2; ++n) acc[a][b][m][n] = (f32x4){0.f, 0.f, 0.f, 0.f};
;     bf16x8 At[4][2], B0[2][2], B1[2][2];
;     const char* cA = (const char*)g.A + (size_t)cur.pm * tstepA + (size_t)cur.ao * 2; const char* cB = (const char*)g.Bt + (size_t)cur.pn * tstepB + (size_t)cur.bo * 2;
;     if constexpr (SP2) {
;         PG8_STAGE(PG8_SB(0, 0), cB, voffB); PG8_STAGE(PG8_SB(0, 1), cB + hstepB, voffB); PG8_STAGE(PG8_SA(0, 0), cA, voffA); PG8_STAGE(PG8_SA(0, 1), cA + hstepA, voffA);
;         if (wr == 1) PG8_BAR;
;         PG8_WAIT_V(2); PG8_BAR;
;         PG8_STAGE(PG8_SB(1, 0), cB + kstep, voffB); PG8_STAGE(PG8_SA(1, 0), cA + kstep, voffA); PG8_STAGE(PG8_SB(1, 1), cB + hstepB + kstep, voffB);
; __global__ void __launch_bounds__(512, 2) fwd_megakernel(Args a) {
;     ...
;     {
;         pg8::Gemm g{U + C_ZP, (const bf16_t*)(a.ws + WS_WOUT), MP, 1024, 2048, LDU, 2048, 0};
;         pg8::PanelOrder S{bid};
;         pg8::EpiResLN E{a.in[0], (const float*)(a.ws + WS_GATEF), a.in[18], a.out, (float*)(a.ws + WS_XBUF), (unsigned*)(a.ws + WS_CTL) + 4096};
.LBB0_1206:
	s_or_b64 exec, exec, s[0:1]
	v_mov_b32_e32 v9, v180
	s_waitcnt lgkmcnt(0)
	s_barrier
	s_mov_b32 s98, 0
	s_cmp_gt_u32 s2, 63
	s_cbranch_scc1 .Lp5_A
	s_mov_b64 s[100:101], s[36:37]
	s_add_u32 s50, s28, 0x1dc00000
	s_addc_u32 s51, s29, 0
	s_mov_b32 s33, 0x10000
	s_mov_b32 s52, 0x14000
	s_mov_b32 s71, 0x18000
	s_mov_b32 s72, 0x1c000
	s_mov_b32 s98, 1
	s_branch .LBB0_1252
.Lp5_A:
	s_mov_b32 s4, 0xfffe0
	v_ashrrev_i32_e32 v1, 31, v9
	v_lshrrev_b32_e32 v1, 26, v1
	v_add_u32_e32 v1, v9, v1
	v_ashrrev_i32_e32 v8, 6, v1
	v_bfe_i32 v1, v9, 27, 1
	v_lshlrev_b32_e32 v0, 4, v9
	v_lshrrev_b32_e32 v1, 22, v1
	v_add_u32_e32 v1, v0, v1
	v_and_b32_e32 v1, 0xfffffc00, v1
	v_sub_u32_e32 v1, v0, v1
	v_lshrrev_b32_e32 v2, 4, v1
	v_bitop3_b32 v1, v2, v1, 32 bitop3:0x6c
	v_ashrrev_i32_e32 v3, 31, v1
	v_lshrrev_b32_e32 v3, 26, v3
	v_add_u32_e32 v3, v1, v3
	v_lshlrev_b32_e32 v2, 3, v8
	v_ashrrev_i32_e32 v10, 6, v3
	v_and_b32_e32 v3, 0xc0, v3
	v_and_b32_e32 v2, -16, v2
	v_sub_u32_e32 v1, v1, v3
	v_mov_b32_e32 v3, 1
	v_add_u32_e32 v2, v10, v2
	v_lshlrev_b32_e32 v4, 5, v8
	v_ashrrev_i16_sdwa v1, v3, sext(v1) dst_sel:DWORD dst_unused:UNUSED_PAD src0_sel:DWORD src1_sel:BYTE_0
	v_and_b32_e32 v11, 32, v4
	v_bfe_i32 v12, v1, 0, 16
	v_lshlrev_b32_e32 v4, 1, v2
	v_lshrrev_b32_e32 v5, 2, v2
	v_and_b32_e32 v6, 3, v10
	s_movk_i32 s1, 0x1c00
	v_add_u32_e32 v1, v11, v12
	v_and_b32_e32 v4, 24, v4
	v_and_b32_e32 v5, 4, v5
	v_and_or_b32 v6, v2, s4, v6
	v_mul_lo_u32 v2, v2, s1
	v_or3_b32 v4, v6, v5, v4
	v_add_lshl_u32 v144, v1, v2, 1
	v_lshlrev_b32_e32 v1, 1, v1
	v_add_u32_e32 v0, 0x2000, v0
	v_lshl_add_u32 v146, v4, 12, v1
	v_ashrrev_i32_e32 v1, 31, v0
	v_lshrrev_b32_e32 v1, 22, v1
	v_add_u32_e32 v1, v0, v1
	v_ashrrev_i32_e32 v13, 10, v1
	v_mul_i32_i24_e32 v1, 0x400, v13
	v_sub_u32_e32 v0, v0, v1
	v_lshrrev_b32_e32 v1, 4, v0
	v_bitop3_b32 v0, v1, v0, 32 bitop3:0x6c
	v_ashrrev_i32_e32 v2, 31, v0
	v_lshrrev_b32_e32 v2, 26, v2
	v_lshlrev_b32_e32 v1, 3, v13
	v_add_u32_e32 v2, v0, v2
	v_and_b32_e32 v1, -16, v1
	v_ashrrev_i32_e32 v14, 6, v2
	v_lshlrev_b32_e32 v4, 5, v13
	v_add_u32_e32 v1, v14, v1
	v_and_b32_e32 v15, 32, v4
	v_and_b32_e32 v4, 3, v14
	s_add_u32 s50, s28, 0x1dc00000
	v_readfirstlane_b32 s0, v9
	v_and_or_b32 v4, v1, s4, v4
	v_readlane_b32 s4, v254, 3
	s_addc_u32 s51, s29, 0
	s_ashr_i32 s5, s0, 6
	v_and_b32_e32 v2, 0xc0, v2
	s_and_b32 s53, s4, 56
	s_ashr_i32 s4, s2, 5
	s_bfe_u32 s55, s2, 0x20003
	v_sub_u32_e32 v0, v0, v2
	s_ashr_i32 s16, s0, 8
	s_add_i32 s53, s53, s4
	s_lshl_b32 s54, s5, 10
	s_lshl_b32 s4, s55, 20
	v_ashrrev_i16_sdwa v0, v3, sext(v0) dst_sel:DWORD dst_unused:UNUSED_PAD src0_sel:DWORD src1_sel:BYTE_0
	s_add_u32 s6, s50, s4
	v_bfe_i32 v16, v0, 0, 16
	v_lshlrev_b32_e32 v2, 1, v1
	v_lshrrev_b32_e32 v3, 2, v1
	s_addc_u32 s7, s51, 0
	s_add_i32 s56, s54, 0
	v_add_u32_e32 v0, v15, v16
	v_and_b32_e32 v2, 24, v2
	v_and_b32_e32 v3, 4, v3
	v_mul_lo_u32 v1, v1, s1
	s_add_i32 m0, s56, 0x10000
	v_or3_b32 v2, v4, v3, v2
	v_add_lshl_u32 v148, v0, v1, 1
	v_lshlrev_b32_e32 v0, 1, v0
	global_load_lds_dwordx4 v146, s[6:7]
	s_add_i32 m0, s56, 0x12000
	v_lshl_add_u32 v150, v2, 12, v0
	s_add_u32 s8, s6, 0x80000
	global_load_lds_dwordx4 v150, s[6:7]
	s_addc_u32 s9, s7, 0
	s_add_i32 m0, s56, 0x14000
	s_mul_i32 s11, s53, 0x380000
	global_load_lds_dwordx4 v146, s[8:9]
	s_add_i32 m0, s56, 0x16000
	s_mul_hi_i32 s10, s53, 0x380000
	v_mov_b32_e32 v153, 0
	global_load_lds_dwordx4 v150, s[8:9]
	s_add_u32 s8, s28, s11
	s_addc_u32 s9, s29, s10
	v_mov_b32_e32 v145, v153
	s_mov_b64 s[10:11], 0x800
	s_add_u32 s42, s8, 0x800
	v_lshl_add_u64 v[0:1], s[8:9], 0, v[144:145]
	s_addc_u32 s43, s9, 0
	v_lshl_add_u64 v[2:3], v[0:1], 0, s[10:11]
	s_mov_b32 m0, s56
	v_mov_b32_e32 v149, v153
	s_add_i32 s57, s56, 0x2000
	global_load_lds_dwordx4 v[2:3], off
	v_lshl_add_u64 v[2:3], s[8:9], 0, v[148:149]
	s_add_u32 s8, s8, 0x1c0800
	v_lshl_add_u64 v[4:5], v[2:3], 0, s[10:11]
	s_mov_b32 m0, s57
	s_addc_u32 s9, s9, 0
	s_add_i32 s58, s56, 0x4000
	global_load_lds_dwordx4 v[4:5], off
	s_mov_b32 m0, s58
	s_add_i32 s59, s56, 0x6000
	global_load_lds_dwordx4 v144, s[8:9]
	s_mov_b32 m0, s59
	v_mov_b32_e32 v147, v153
	global_load_lds_dwordx4 v148, s[8:9]
	v_mov_b32_e32 v151, v153
	s_cmp_eq_u32 s16, 1
	v_lshl_add_u64 v[4:5], s[6:7], 0, v[146:147]
	s_cselect_b64 s[8:9], -1, 0
	s_cmp_lg_u32 s16, 1
	v_lshl_add_u64 v[6:7], s[6:7], 0, v[150:151]
	s_cbranch_scc1 .LBB0_1208
	s_barrier

;     __device__ bool next(int i, Unit& u) const { if (i >= 2) return false; const int x = c & 7, j = c >> 3; u.pm = 64 * i + 8 * x + (j >> 2); u.pn = j & 3; u.ao = 0; u.bo = 0; u.ks = 0; return true; }
;     __device__ bool next(int i, Unit& u) const { if (i >= 1 || c >= 64) return false; u.pm = 128 + (c & 3); u.pn = (c >> 2) & 3; u.ks = c >> 4; u.ao = u.ks * 512; u.bo = u.ks * 512; return true; }
; template <class Epi, class Sched, bool ALIGN_EPI, bool SP2>
; __device__ __forceinline__ void gemm_phase(LAS unsigned char* lds, const Gemm g, const Sched& S, const Epi& E) {
;     ...
;     const int wid = __builtin_amdgcn_readfirstlane(tid >> 6), lane = tid & 63, wr = wid >> 2, wc = wid & 3, fr = lane & 15, fq = lane >> 4;
;     const int K = g.K, nt = K / BK, lda = g.lda;
;     unsigned voffA[2], voffB[2];
; #pragma unroll
;     for (int i = 0; i < 2; ++i) { int R, C; stage_rc(tid * 16 + i * 8192, R, C); const int Rb = (R & ~31) + perm32(R & 31);
;         voffA[i] = (unsigned)(R * lda + C) * 2u; voffB[i] = (unsigned)(Rb * g.ldb + C) * 2u; }
;     const size_t kstep = (size_t)(BK * 2);
;     const size_t hstepA = (size_t)HALF * lda * 2, hstepB = (size_t)HALF * g.ldb * 2;
;     const size_t tstepA = 2 * hstepA, tstepB = 2 * hstepB;
;     const unsigned ldsw = (unsigned)wid * 1024u;
;     const int aoff = lds_byte(wr * 64 + fr, fq * 8), boff = lds_byte(wc * 32 + fr, fq * 8);
;     ...
;     Unit cur, nxt; int ui = 0;
;     if (!S.next(0, cur)) return;
;     f32x4 acc[2][2][4][2];
; #pragma unroll
;     for (int a = 0; a < 2; ++a)
; #pragma unroll
;         for (int b = 0; b < 2; ++b)
; #pragma unroll
;             for (int m = 0; m < 4; ++m)
; #pragma unroll
;                 for (int n = 0; n < 2; ++n) acc[a][b][m][n] = (f32x4){0.f, 0.f, 0.f, 0.f};
;     bf16x8 At[4][2], B0[2][2], B1[2][2];
;     const char* cA = (const char*)g.A + (size_t)cur.pm * tstepA + (size_t)cur.ao * 2; const char* cB = (const char*)g.Bt + (size_t)cur.pn * tstepB + (size_t)cur.bo * 2;
;     if constexpr (SP2) {
;         PG8_STAGE(PG8_SB(0, 0), cB, voffB); PG8_STAGE(PG8_SB(0, 1), cB + hstepB, voffB); PG8_STAGE(PG8_SA(0, 0), cA, voffA); PG8_STAGE(PG8_SA(0, 1), cA + hstepA, voffA);
;         if (wr == 1) PG8_BAR;
;         PG8_WAIT_V(2); PG8_BAR;
;         PG8_STAGE(PG8_SB(1, 0), cB + kstep, voffB); PG8_STAGE(PG8_SA(1, 0), cA + kstep, voffA); PG8_STAGE(PG8_SB(1, 1), cB + hstepB + kstep, voffB);
.LBB0_1252:
	s_waitcnt vmcnt(0)
	v_mov_b32_e32 v12, v180
	s_barrier
	s_cmp_eq_u32 s98, 2
	s_cbranch_scc1 .LBB0_1260
	s_cmp_gt_i32 s2, 63
	v_readfirstlane_b32 s21, v12
	s_cbranch_scc1 .LBB0_1260
	v_lshlrev_b32_e32 v0, 4, v12
	v_add_u32_e32 v1, 0x2000, v0
	v_ashrrev_i32_e32 v2, 31, v1
	v_lshrrev_b32_e32 v2, 22, v2
	v_add_u32_e32 v2, v1, v2
	v_ashrrev_i32_e32 v8, 10, v2
	v_mul_i32_i24_e32 v2, 0x400, v8
	v_sub_u32_e32 v1, v1, v2
	v_lshrrev_b32_e32 v2, 4, v1
	v_bitop3_b32 v1, v2, v1, 32 bitop3:0x6c
	v_ashrrev_i32_e32 v2, 31, v1
	v_lshrrev_b32_e32 v2, 26, v2
	v_add_u32_e32 v2, v1, v2
	v_lshlrev_b32_e32 v3, 3, v8
	v_ashrrev_i32_e32 v9, 6, v2
	v_and_b32_e32 v3, -16, v3
	v_add_u32_e32 v3, v9, v3
	v_and_b32_e32 v4, 3, v9
	s_mov_b32 s5, 0xfffe0
	v_lshrrev_b32_e32 v5, 2, v3
	v_lshlrev_b32_e32 v6, 1, v3
	v_and_b32_e32 v2, 0xc0, v2
	v_and_or_b32 v4, v3, s5, v4
	v_and_b32_e32 v5, 4, v5
	v_and_b32_e32 v6, 24, v6
	v_sub_u32_e32 v1, v1, v2
	v_mov_b32_e32 v2, 1
	v_or3_b32 v4, v4, v5, v6
	v_lshlrev_b32_e32 v5, 5, v8
	v_ashrrev_i16_sdwa v1, v2, sext(v1) dst_sel:DWORD dst_unused:UNUSED_PAD src0_sel:DWORD src1_sel:BYTE_0
	v_and_b32_e32 v10, 32, v5
	v_bfe_i32 v11, v1, 0, 16
	s_movk_i32 s13, 0x1c00
	v_add_u32_e32 v1, v10, v11
	v_mul_lo_u32 v3, v3, s13
	v_lshlrev_b32_e32 v5, 1, v1
	v_add_lshl_u32 v130, v1, v3, 1
	v_bfe_i32 v1, v12, 27, 1
	v_lshrrev_b32_e32 v1, 22, v1
	v_add_u32_e32 v1, v0, v1
	v_and_b32_e32 v1, 0xfffffc00, v1
	v_sub_u32_e32 v0, v0, v1
	v_lshrrev_b32_e32 v1, 4, v0
	v_ashrrev_i32_e32 v3, 31, v12
	v_bitop3_b32 v0, v1, v0, 32 bitop3:0x6c
	v_lshrrev_b32_e32 v3, 26, v3
	v_ashrrev_i32_e32 v1, 31, v0
	v_add_u32_e32 v3, v12, v3
	v_lshrrev_b32_e32 v1, 26, v1
	v_ashrrev_i32_e32 v14, 6, v3
	v_add_u32_e32 v1, v0, v1
	v_lshlrev_b32_e32 v3, 3, v14
	s_ashr_i32 s0, s2, 4
	v_ashrrev_i32_e32 v13, 6, v1
	v_and_b32_e32 v3, -16, v3
	s_lshl_b32 s4, s0, 9
	v_lshl_add_u32 v128, v4, 12, v5
	v_add_u32_e32 v3, v13, v3
	v_and_b32_e32 v4, 3, v13
	s_ashr_i32 s6, s21, 6
	s_and_b32 s8, s2, 3
	s_bfe_u32 s1, s2, 0x20002
	v_and_or_b32 v4, v3, s5, v4
	v_lshrrev_b32_e32 v5, 2, v3
	v_lshlrev_b32_e32 v6, 1, v3
	v_and_b32_e32 v1, 0xc0, v1
	s_ashr_i32 s5, s4, 31
	s_ashr_i32 s7, s21, 8
	s_lshl_b32 s12, s6, 10
	s_or_b32 s20, s8, 0x80
	v_and_b32_e32 v5, 4, v5
	v_and_b32_e32 v6, 24, v6
	v_sub_u32_e32 v0, v0, v1
	s_lshl_b64 s[10:11], s[4:5], 1
	s_lshl_b32 s14, s1, 20
	v_or3_b32 v4, v4, v5, v6
	v_lshlrev_b32_e32 v5, 5, v14
	v_ashrrev_i16_sdwa v0, v2, sext(v0) dst_sel:DWORD dst_unused:UNUSED_PAD src0_sel:DWORD src1_sel:BYTE_0
	s_add_u32 s4, s50, s14
	v_and_b32_e32 v15, 32, v5
	v_bfe_i32 v16, v0, 0, 16
	s_addc_u32 s5, s51, 0
	v_add_u32_e32 v0, v15, v16
	s_add_u32 s4, s4, s10
	v_lshlrev_b32_e32 v1, 1, v0
	s_addc_u32 s5, s5, s11
	s_add_i32 s35, s12, 0
	v_lshl_add_u32 v132, v4, 12, v1
	s_add_i32 m0, s35, 0x10000
	s_mul_i32 s9, s20, 0x380000
	global_load_lds_dwordx4 v132, s[4:5]
	s_add_i32 m0, s35, 0x12000
	s_add_u32 s9, s28, s9
	s_addc_u32 s15, s29, 0
	s_add_u32 s16, s4, 0x80000
	global_load_lds_dwordx4 v128, s[4:5]
	s_addc_u32 s17, s5, 0
	s_add_i32 m0, s35, 0x14000
	v_mul_lo_u32 v1, v3, s13
	global_load_lds_dwordx4 v132, s[16:17]
	s_add_i32 m0, s35, 0x16000
	v_mov_b32_e32 v133, 0
	global_load_lds_dwordx4 v128, s[16:17]
	s_add_u32 s16, s9, s10
	v_add_lshl_u32 v134, v0, v1, 1
	s_addc_u32 s17, s15, s11
	v_mov_b32_e32 v135, v133
	s_mov_b64 s[40:41], 0x800
	v_lshl_add_u64 v[0:1], s[16:17], 0, v[134:135]
	v_lshl_add_u64 v[2:3], v[0:1], 0, s[40:41]
	s_mov_b32 m0, s35
	v_mov_b32_e32 v131, v133
	s_add_u32 s36, s16, 0x800
	global_load_lds_dwordx4 v[2:3], off
	v_lshl_add_u64 v[2:3], s[16:17], 0, v[130:131]
	s_addc_u32 s37, s17, 0
	v_lshl_add_u64 v[4:5], v[2:3], 0, s[40:41]
	s_add_i32 s40, s35, 0x2000
	s_add_u32 s16, s16, 0x1c0800
	s_mov_b32 m0, s40
	s_addc_u32 s17, s17, 0
	s_add_i32 s41, s35, 0x4000
	global_load_lds_dwordx4 v[4:5], off
	s_mov_b32 m0, s41
	s_add_i32 s42, s35, 0x6000
	global_load_lds_dwordx4 v134, s[16:17]
	s_mov_b32 m0, s42
	v_mov_b32_e32 v129, v133
	global_load_lds_dwordx4 v130, s[16:17]
	v_lshl_add_u64 v[4:5], s[4:5], 0, v[132:133]
	s_cmp_lg_u32 s7, 1
	v_lshl_add_u64 v[6:7], s[4:5], 0, v[128:129]
	s_cbranch_scc1 .LBB0_1255
	s_barrier

; __global__ void __launch_bounds__(512, 2) fwd_megakernel(Args a) {
;     ...
;         pg8::gemm_phase<pg8::EpiPart, pg8::SampleOrder, true, true>(L, g2, S2, E2);
;     }
;     xcd_barrier(xbar);
.LBB0_1260:
	s_cmp_lg_u32 s98, 1
	s_cbranch_scc1 .Lp5_end
	s_mov_b32 s98, 2
	s_mov_b64 s[36:37], s[100:101]
	v_mov_b32_e32 v9, v180
	s_branch .Lp5_A

; __global__ void __launch_bounds__(512, 2) fwd_megakernel(Args a) {
	.amdhsa_kernel _Z14fwd_megakernel4Args
		.amdhsa_group_segment_fixed_size 0
		.amdhsa_private_segment_fixed_size 0
		.amdhsa_kernarg_size 424
		.amdhsa_user_sgpr_count 2
		.amdhsa_user_sgpr_dispatch_ptr 0
		.amdhsa_user_sgpr_queue_ptr 0
		.amdhsa_user_sgpr_kernarg_segment_ptr 1
		.amdhsa_user_sgpr_dispatch_id 0
		.amdhsa_user_sgpr_kernarg_preload_length 0
		.amdhsa_user_sgpr_kernarg_preload_offset 0
		.amdhsa_user_sgpr_private_segment_size 0
		.amdhsa_uses_dynamic_stack 0
		.amdhsa_enable_private_segment 0
		.amdhsa_system_sgpr_workgroup_id_x 1
		.amdhsa_system_sgpr_workgroup_id_y 0
		.amdhsa_system_sgpr_workgroup_id_z 0
		.amdhsa_system_sgpr_workgroup_info 0
		.amdhsa_system_vgpr_workitem_id 2
		.amdhsa_next_free_vgpr 255
		.amdhsa_next_free_sgpr 102
		.amdhsa_accum_offset 256
		.amdhsa_reserve_vcc 1
		.amdhsa_float_round_mode_32 0
		.amdhsa_float_round_mode_16_64 0
		.amdhsa_float_denorm_mode_32 3
		.amdhsa_float_denorm_mode_16_64 3
		.amdhsa_dx10_clamp 1
		.amdhsa_ieee_mode 1
		.amdhsa_fp16_overflow 0
		.amdhsa_tg_split 0
		.amdhsa_exception_fp_ieee_invalid_op 0
		.amdhsa_exception_fp_denorm_src 0
		.amdhsa_exception_fp_ieee_div_zero 0
		.amdhsa_exception_fp_ieee_overflow 0
		.amdhsa_exception_fp_ieee_underflow 0
		.amdhsa_exception_fp_ieee_inexact 0
		.amdhsa_exception_int_div_zero 0
	.end_amdhsa_kernel

; __global__ void __launch_bounds__(512, 2) fwd_megakernel(Args a) {
amdhsa.kernels:
  - .agpr_count:     0
    .args:
      - .offset:         0
        .size:           168
        .value_kind:     by_value
      - .offset:         168
        .size:           4
        .value_kind:     hidden_block_count_x
      - .offset:         172
        .size:           4
        .value_kind:     hidden_block_count_y
      - .offset:         176
        .size:           4
        .value_kind:     hidden_block_count_z
      - .offset:         180
        .size:           2
        .value_kind:     hidden_group_size_x
      - .offset:         182
        .size:           2
        .value_kind:     hidden_group_size_y
      - .offset:         184
        .size:           2
        .value_kind:     hidden_group_size_z
      - .offset:         186
        .size:           2
        .value_kind:     hidden_remainder_x
      - .offset:         188
        .size:           2
        .value_kind:     hidden_remainder_y
      - .offset:         190
        .size:           2
        .value_kind:     hidden_remainder_z
      - .offset:         208
        .size:           8
        .value_kind:     hidden_global_offset_x
      - .offset:         216
        .size:           8
        .value_kind:     hidden_global_offset_y
      - .offset:         224
        .size:           8
        .value_kind:     hidden_global_offset_z
      - .offset:         232
        .size:           2
        .value_kind:     hidden_grid_dims
      - .offset:         256
        .size:           8
        .value_kind:     hidden_multigrid_sync_arg
      - .offset:         288
        .size:           4
        .value_kind:     hidden_dynamic_lds_size
    .group_segment_fixed_size: 0
    .kernarg_segment_align: 8
    .kernarg_segment_size: 424
    .language:       OpenCL C
    .language_version:
      - 2
      - 0
    .max_flat_workgroup_size: 512
    .name:           _Z14fwd_megakernel4Args
    .private_segment_fixed_size: 0
    .sgpr_count:     108
    .sgpr_spill_count: 4
    .symbol:         _Z14fwd_megakernel4Args.kd
    .uniform_work_group_size: 1
    .uses_dynamic_stack: false
    .vgpr_count:     255
    .vgpr_spill_count: 0
    .wavefront_size: 64
